# loop-edge edits: back-edge counter/pointer updates and K address calc moved before the loop barrier; first K reads issued ahead of the bias-class test chain
# speedup vs baseline: 1.0188x; 1.0079x over previous
.LBB0_512:
	s_waitcnt lgkmcnt(2)
	v_mfma_f32_32x32x16_bf16 v[50:65], v[162:165], v[122:125], v[50:65]
	ds_read_b64_tr_b16 v[126:127], v222 offset:1024
	ds_read_b64_tr_b16 v[128:129], v222 offset:3072
	v_mfma_f32_16x16x32_bf16 v[240:243], v[114:117], v[236:239], v[240:243]
	v_cndmask_b32_e64 v166, v221, v223, s[4:5]
	v_exp_f32_e32 v98, v98
	v_exp_f32_e32 v99, v99
	s_waitcnt lgkmcnt(2)
	v_mfma_f32_32x32x16_bf16 v[66:81], v[162:165], v[118:121], v[66:81]
	ds_read_b64_tr_b16 v[122:123], v222 offset:1536
	ds_read_b64_tr_b16 v[124:125], v222 offset:3584
	v_exp_f32_e32 v100, v100
	v_exp_f32_e32 v101, v101
	s_waitcnt lgkmcnt(2)
	v_mfma_f32_32x32x16_bf16 v[2:17], v[162:165], v[126:129], v[2:17]
	ds_read_b64_tr_b16 v[118:119], v222 offset:4096
	ds_read_b64_tr_b16 v[120:121], v222 offset:6144
	v_exp_f32_e32 v102, v102
	v_exp_f32_e32 v103, v103
	s_waitcnt lgkmcnt(2)
	v_mfma_f32_32x32x16_bf16 v[18:33], v[162:165], v[122:125], v[18:33]
	ds_read_b64_tr_b16 v[126:127], v222 offset:4608
	ds_read_b64_tr_b16 v[128:129], v222 offset:6656
	v_exp_f32_e32 v104, v104
	v_exp_f32_e32 v105, v105
	s_waitcnt lgkmcnt(2)
	v_mfma_f32_32x32x16_bf16 v[50:65], v[134:137], v[118:121], v[50:65]
	ds_read_b64_tr_b16 v[122:123], v222 offset:5120
	ds_read_b64_tr_b16 v[124:125], v222 offset:7168
	v_exp_f32_e32 v106, v106
	v_exp_f32_e32 v107, v107
	s_waitcnt lgkmcnt(2)
	v_mfma_f32_32x32x16_bf16 v[66:81], v[134:137], v[126:129], v[66:81]
	ds_read_b64_tr_b16 v[118:119], v222 offset:5632
	ds_read_b64_tr_b16 v[120:121], v222 offset:7680
	v_exp_f32_e32 v108, v108
	v_exp_f32_e32 v109, v109
	s_waitcnt lgkmcnt(2)
	v_mfma_f32_32x32x16_bf16 v[2:17], v[134:137], v[122:125], v[2:17]
	ds_read_b64_tr_b16 v[126:127], v222 offset:8192
	ds_read_b64_tr_b16 v[128:129], v222 offset:10240
	v_exp_f32_e32 v110, v110
	v_exp_f32_e32 v111, v111
	s_waitcnt lgkmcnt(2)
	v_mfma_f32_32x32x16_bf16 v[18:33], v[134:137], v[118:121], v[18:33]
	ds_read_b64_tr_b16 v[122:123], v222 offset:8704
	ds_read_b64_tr_b16 v[124:125], v222 offset:10752
	v_exp_f32_e32 v112, v112
	v_exp_f32_e32 v113, v113
	s_waitcnt lgkmcnt(2)
	v_mfma_f32_32x32x16_bf16 v[50:65], v[130:133], v[126:129], v[50:65]
	ds_read_b64_tr_b16 v[118:119], v222 offset:9216
	ds_read_b64_tr_b16 v[120:121], v222 offset:11264
	v_exp_f32_e32 v82, v82
	v_exp_f32_e32 v83, v83
	s_waitcnt lgkmcnt(2)
	v_mfma_f32_32x32x16_bf16 v[66:81], v[130:133], v[122:125], v[66:81]
	ds_read_b64_tr_b16 v[126:127], v222 offset:9728
	ds_read_b64_tr_b16 v[128:129], v222 offset:11776
	v_exp_f32_e32 v84, v84
	v_exp_f32_e32 v85, v85
	s_waitcnt lgkmcnt(2)
	v_mfma_f32_32x32x16_bf16 v[2:17], v[130:133], v[118:121], v[2:17]
	ds_read_b64_tr_b16 v[122:123], v222 offset:12288
	ds_read_b64_tr_b16 v[124:125], v222 offset:14336
	v_exp_f32_e32 v86, v86
	v_exp_f32_e32 v87, v87
	s_waitcnt lgkmcnt(2)
	v_mfma_f32_32x32x16_bf16 v[18:33], v[130:133], v[126:129], v[18:33]
	ds_read_b64_tr_b16 v[118:119], v222 offset:12800
	ds_read_b64_tr_b16 v[120:121], v222 offset:14848
	v_exp_f32_e32 v88, v88
	v_exp_f32_e32 v89, v89
	s_waitcnt lgkmcnt(2)
	v_mfma_f32_32x32x16_bf16 v[50:65], v[114:117], v[122:125], v[50:65]
	ds_read_b64_tr_b16 v[126:127], v222 offset:13312
	ds_read_b64_tr_b16 v[128:129], v222 offset:15360
	v_exp_f32_e32 v90, v90
	v_exp_f32_e32 v91, v91
	s_waitcnt lgkmcnt(2)
	v_mfma_f32_32x32x16_bf16 v[66:81], v[114:117], v[118:121], v[66:81]
	ds_read_b64_tr_b16 v[122:123], v222 offset:13824
	ds_read_b64_tr_b16 v[124:125], v222 offset:15872
	v_exp_f32_e32 v92, v92
	v_exp_f32_e32 v93, v93
	s_waitcnt lgkmcnt(2)
	v_mfma_f32_32x32x16_bf16 v[2:17], v[114:117], v[126:129], v[2:17]
	v_exp_f32_e32 v94, v94
	v_exp_f32_e32 v95, v95
	s_waitcnt lgkmcnt(0)
	v_mfma_f32_32x32x16_bf16 v[18:33], v[114:117], v[122:125], v[18:33]
	v_exp_f32_e32 v96, v96
	v_exp_f32_e32 v97, v97
	s_add_i32 s4, s9, 1
	s_cmp_lg_u32 s9, 4
	s_cselect_b32 s14, s4, 0
	s_add_i32 s67, s67, 2
	s_addk_i32 s66, 0x80
	s_add_u32 s40, s40, 0x8000
	s_addc_u32 s41, s41, 0
	s_add_u32 s46, s46, 0x4000
	s_addc_u32 s47, s47, 0
	v_add_u32_e32 v218, 0x200, v218
	s_and_b64 vcc, exec, s[50:51]
	s_waitcnt vmcnt(0) lgkmcnt(0)
	s_barrier
	s_cbranch_vccnz .LBB0_525
.LBB0_513:
	v_lshl_add_u32 v169, s14, 13, v205
	ds_read_b128 v[114:117], v169
	ds_read_b128 v[220:223], v169 offset:512
	s_add_i32 s4, s66, 0xffffff02
	s_cmpk_lt_i32 s4, 0xff42
	s_cselect_b64 vcc, -1, 0
	s_cmpk_gt_i32 s4, 0x9e
	s_cselect_b64 s[4:5], -1, 0
	v_cndmask_b32_e64 v253, 0, v207, s[4:5]
	v_cndmask_b32_e32 v168, v253, v206, vcc
	v_cmp_eq_f32_e32 vcc, v168, v166
	v_cmp_neq_f32_e64 s[4:5], v168, v166
	s_cbranch_vccnz .LBB0_515
	v_sub_f32_e32 v34, v168, v217
	v_mov_b32_e32 v35, v34
	v_mov_b32_e32 v36, v34
	v_mov_b32_e32 v37, v34
	v_mov_b32_e32 v38, v34
	v_mov_b32_e32 v39, v34
	v_mov_b32_e32 v40, v34
	v_mov_b32_e32 v41, v34
	v_mov_b32_e32 v42, v34
	v_mov_b32_e32 v43, v34
	v_mov_b32_e32 v44, v34
	v_mov_b32_e32 v45, v34
	v_mov_b32_e32 v46, v34
	v_mov_b32_e32 v47, v34
	v_mov_b32_e32 v48, v34
	v_mov_b32_e32 v49, v34
.LBB0_515:
	s_lshl_b32 s9, s9, 14
	v_add_u32_e32 v167, s9, v204
	s_waitcnt lgkmcnt(1)
	v_mfma_f32_32x32x16_bf16 v[130:145], v[114:117], v[158:161], v[34:49]
	ds_read_b128 v[224:227], v169 offset:2048
	v_cvt_pk_bf16_f32 v162, v98, v99
	v_cvt_pk_bf16_f32 v163, v100, v101
	ds_read_b128 v[98:101], v169 offset:2560
	v_cvt_pk_bf16_f32 v164, v102, v103
	s_waitcnt lgkmcnt(2)
	v_mfma_f32_32x32x16_bf16 v[114:129], v[220:223], v[158:161], v[34:49]
	v_cvt_pk_bf16_f32 v165, v104, v105
	s_waitcnt lgkmcnt(1)
	v_mfma_f32_32x32x16_bf16 v[130:145], v[224:227], v[154:157], v[130:145]
	ds_read_b128 v[220:223], v169 offset:4096
	v_mfma_f32_16x16x32_bf16 v[240:243], v[162:165], v[236:239], v[240:243]
	v_cvt_pk_bf16_f32 v102, v106, v107
	v_cvt_pk_bf16_f32 v103, v108, v109
	s_waitcnt lgkmcnt(1)
	v_mfma_f32_32x32x16_bf16 v[114:129], v[98:101], v[154:157], v[114:129]
	ds_read_b128 v[106:109], v169 offset:4608
	v_cvt_pk_bf16_f32 v104, v110, v111
	v_cvt_pk_bf16_f32 v105, v112, v113
	s_waitcnt lgkmcnt(1)
	v_mfma_f32_32x32x16_bf16 v[130:145], v[220:223], v[150:153], v[130:145]
	ds_read_b128 v[110:113], v169 offset:6144
	v_mfma_f32_16x16x32_bf16 v[240:243], v[102:105], v[236:239], v[240:243]
	v_cvt_pk_bf16_f32 v98, v82, v83
	v_cvt_pk_bf16_f32 v99, v84, v85
	s_waitcnt lgkmcnt(1)
	v_mfma_f32_32x32x16_bf16 v[114:129], v[106:109], v[150:153], v[114:129]
	ds_read_b128 v[220:223], v169 offset:6656
	v_cvt_pk_bf16_f32 v100, v86, v87
	v_cvt_pk_bf16_f32 v101, v88, v89
	s_waitcnt lgkmcnt(1)
	v_mfma_f32_32x32x16_bf16 v[130:145], v[110:113], v[146:149], v[130:145]
	v_cvt_pk_bf16_f32 v82, v90, v91
	v_mfma_f32_16x16x32_bf16 v[240:243], v[98:101], v[236:239], v[240:243]
	v_cvt_pk_bf16_f32 v83, v92, v93
	ds_read_b64_tr_b16 v[86:87], v167
	ds_read_b64_tr_b16 v[88:89], v167 offset:2048
	s_waitcnt lgkmcnt(2)
	v_mfma_f32_32x32x16_bf16 v[114:129], v[220:223], v[146:149], v[114:129]
	v_cvt_pk_bf16_f32 v84, v94, v95
	v_cvt_pk_bf16_f32 v85, v96, v97
	ds_read_b64_tr_b16 v[90:91], v167 offset:512
	ds_read_b64_tr_b16 v[92:93], v167 offset:2560
	s_add_i32 s9, s67, -1
	s_cmp_ge_u32 s9, s55
	s_cbranch_scc0 .LBB0_523
	s_cmp_ge_u32 s67, s55
	s_cselect_b64 s[50:51], -1, 0
	s_and_b64 vcc, exec, s[50:51]
	s_cbranch_vccz .LBB0_524

; #define LAS __attribute__((address_space(3)))
; #define WAIT_BAR() asm volatile("s_waitcnt vmcnt(0) lgkmcnt(0)\n\ts_barrier" ::: "memory")
; #define WAIT_BAR() asm volatile("s_waitcnt vmcnt(0) lgkmcnt(0)\n\ts_barrier" ::: "memory")
; template <int NCB, bool DIFF, bool STAT>
; __device__ __forceinline__ void attn_unit(LAS char* lds, const Params& P, int s, int head, int qb, float sref) {
;     ...
;         const unsigned dvoff = (unsigned)(wid * 1024 + lane * 16);
;         const unsigned kdst = lds0 + L_K + wid * 1024, vdst = lds0 + L_V + wid * 1024;
;     ...
;         __syncthreads();
;         DMA(0, 0); DMA(1, 1); DMA(2, 2);
;         bf16x8 qr[4];
; #pragma unroll
;         for (int d0 = 0; d0 < 4; ++d0) qr[d0] = *(const bf16x8*)(Qw + (size_t)r32 * 64 + d0 * 16 + hi * 8);
;         constexpr bool ZREF = STAT && !DIFF;
;         float m_reg = (STAT && !ZREF) ? sref : 0.f, l_reg = 0.f, cb = 0.f; bool moved = true;
;         if constexpr (STAT && DIFF) {
;             float q2 = 0.f;
; #pragma unroll
;             for (int d0 = 0; d0 < 4; ++d0)
; #pragma unroll
;                 for (int i = 0; i < 8; ++i) { const float f = __builtin_bit_cast(float, (unsigned)(unsigned short)qr[d0][i] << 16); q2 += f * f; }
;             { auto rr = __builtin_amdgcn_permlane32_swap(__float_as_uint(q2), __float_as_uint(q2), false, false); q2 = __uint_as_float(rr[0]) + __uint_as_float(rr[1]); }
;             const float kn2 = __uint_as_float(((const unsigned*)(ws + WS_BAR))[3800 + s * 8 + head * 2 + mp]);
;             m_reg = __builtin_sqrtf(q2 * kn2) * 1.001f + 0.01f + sref;
;         }
;         f32x16 negm;
; #pragma unroll
;         for (int d = 0; d < NCB; ++d) o[d] = f32x16{};
;         f32x16 pA0, pA1, pB0, pB1; float alA = 1.f, alB = 1.f;
;         u32x4 pw[4];
;         int bm = 0, ix = 0;
;         WAIT_BAR();
;         BMODE(0); NEGM();
;         { const LAS char* kp_ = kp0;
; #pragma unroll
;           for (int d0 = 0; d0 < 4; ++d0) { const bf16x8 b0 = *(const LAS bf16x8*)(kp_ + d0 * 2048), b1 = *(const LAS bf16x8*)(kp_ + d0 * 2048 + 512);
;               if (d0 == 0) { if constexpr (ZREF) { pA0 = MFMA32(b0, qr[0], f32x16{}); pA1 = MFMA32(b1, qr[0], f32x16{}); } else { pA0 = MFMA32(b0, qr[0], negm); pA1 = MFMA32(b1, qr[0], negm); } } else { pA0 = MFMA32(b0, qr[d0], pA0); pA1 = MFMA32(b1, qr[d0], pA1); } } }
.LBB0_588:
	v_readlane_b32 s4, v254, 45
	v_readlane_b32 s5, v254, 46
	s_lshl_b32 s8, s64, 14
	s_nop 3
	global_load_dword v1, v0, s[4:5]
	s_lshl_b32 s4, s64, 12
	s_add_i32 s9, s4, 0x6000
	s_cmp_lt_u32 s64, 2
	s_cselect_b64 s[4:5], -1, 0
	s_and_b64 s[6:7], s[4:5], exec
	s_mov_b32 s6, 0x42200000
	s_cselect_b32 s48, 0x100, 64
	s_cselect_b32 s14, s8, s9
	s_lshl_b32 s42, s63, 8
	s_waitcnt vmcnt(0)
	v_cmp_nge_f32_e32 vcc, s6, v1
	s_cbranch_vccnz .LBB0_595
	v_mov_b32_e32 v42, v230
	s_lshl_b64 s[6:7], s[14:15], 3
	v_readfirstlane_b32 s9, v42
	s_ashr_i32 s8, s9, 6
	s_lshl_b32 s43, s8, 5
	s_add_i32 s43, s43, s42
	s_and_b64 s[12:13], s[4:5], exec
	s_mov_b32 s73, s15
	s_cselect_b32 s40, 14, 12
	s_lshl_b64 s[12:13], s[72:73], s40
	s_add_u32 s6, s6, s12
	s_addc_u32 s7, s7, s13
	s_ashr_i32 s12, s43, 31
	s_add_u32 s6, s6, s43
	s_addc_u32 s7, s7, s12
	s_lshl_b64 s[6:7], s[6:7], 7
	s_add_u32 s12, s92, s6
	s_addc_u32 s13, s93, s7
	s_lshr_b32 s6, s72, 2
	s_mov_b32 s7, s15
	s_lshl_b64 s[6:7], s[6:7], s40
	s_lshl_b64 s[40:41], s[14:15], 8
	s_lshl_b64 s[6:7], s[6:7], 7
	s_add_u32 s6, s40, s6
	s_addc_u32 s7, s41, s7
	v_readlane_b32 s16, v254, 47
	s_add_u32 s40, s16, s6
	v_readlane_b32 s16, v254, 48
	s_addc_u32 s41, s16, s7
	v_readlane_b32 s16, v254, 49
	v_and_b32_e32 v133, 63, v42
	s_add_u32 s6, s16, s6
	v_readlane_b32 s16, v254, 50
	v_lshlrev_b32_e32 v43, 4, v133
	s_addc_u32 s7, s16, s7
	s_lshl_b32 s47, s8, 10
	v_or_b32_e32 v134, s47, v43
	s_add_i32 s46, s47, s65
	s_add_i32 s47, s47, 0
	s_add_u32 s50, s40, 0x2000
	s_addc_u32 s51, s41, 0
	s_add_u32 s54, s6, 0x2000
	s_addc_u32 s55, s7, 0
	s_add_u32 s56, s40, 0x4000
	v_and_b32_e32 v132, 31, v42
	s_addc_u32 s57, s41, 0
	s_barrier
	s_mov_b32 s8, m0
	s_mov_b32 m0, s46
	s_nop 0
	global_load_lds_dwordx4 v134, s[40:41]
	s_mov_b32 m0, s8
	s_add_u32 s58, s6, 0x4000
	v_lshlrev_b32_e32 v2, 7, v132
	v_mov_b32_e32 v3, v0
	s_mov_b32 s8, m0
	s_mov_b32 m0, s47
	s_nop 0
	global_load_lds_dwordx4 v134, s[6:7]
	s_mov_b32 m0, s8
	s_addc_u32 s59, s7, 0
	v_lshl_add_u64 v[2:3], s[12:13], 0, v[2:3]
	s_add_i32 s8, s47, 0x16000
	s_mov_b32 s12, m0
	s_mov_b32 m0, s8
	s_nop 0
	global_load_lds_dwordx4 v134, s[50:51]
	s_mov_b32 m0, s12
	v_bfe_u32 v150, v42, 5, 1
	s_add_i32 s8, s47, 0x4000
	s_mov_b32 s12, m0
	s_mov_b32 m0, s8
	s_nop 0
	global_load_lds_dwordx4 v134, s[54:55]
	s_mov_b32 m0, s12
	v_lshlrev_b32_e32 v148, 4, v150
	v_mov_b32_e32 v149, v0
	s_add_i32 s8, s47, 0x18000
	s_mov_b32 s12, m0
	s_mov_b32 m0, s8
	s_nop 0
	global_load_lds_dwordx4 v134, s[56:57]
	s_mov_b32 m0, s12
	v_lshl_add_u64 v[6:7], v[2:3], 0, v[148:149]
	s_add_i32 s8, s47, 0x8000
	s_mov_b32 s12, m0
	s_mov_b32 m0, s8
	s_nop 0
	global_load_lds_dwordx4 v134, s[58:59]
	s_mov_b32 m0, s12
	global_load_dwordx4 v[124:127], v[6:7], off
	global_load_dwordx4 v[120:123], v[6:7], off offset:32
	global_load_dwordx4 v[116:119], v[6:7], off offset:64
	global_load_dwordx4 v[112:115], v[6:7], off offset:96
	v_mov_b32_e32 v2, v0
	v_mov_b32_e32 v3, v0
	v_mov_b32_e32 v4, v0
	v_mov_b32_e32 v5, v0
	v_mov_b32_e32 v6, v0
	v_mov_b32_e32 v7, v0
	v_mov_b32_e32 v8, v0
	v_mov_b32_e32 v9, v0
	v_mov_b32_e32 v10, v0
	v_mov_b32_e32 v11, v0
	v_mov_b32_e32 v12, v0
	v_mov_b32_e32 v13, v0
	v_mov_b32_e32 v14, v0
	v_mov_b32_e32 v15, v0
	v_mov_b32_e32 v1, v0
	v_mov_b64_e32 v[16:17], v[14:15]
	v_mov_b64_e32 v[14:15], v[12:13]
	v_mov_b64_e32 v[12:13], v[10:11]
	v_mov_b64_e32 v[10:11], v[8:9]
	v_mov_b64_e32 v[8:9], v[6:7]
	v_mov_b64_e32 v[6:7], v[4:5]
	v_mov_b64_e32 v[4:5], v[2:3]
	v_mov_b64_e32 v[2:3], v[0:1]
	v_lshlrev_b32_e32 v1, 10, v150
	v_lshlrev_b32_e32 v18, 4, v132
	v_add3_u32 v135, s65, v1, v18
	s_waitcnt vmcnt(0) lgkmcnt(0)
	s_barrier
	ds_read_b128 v[2:5], v135
	ds_read_b128 v[18:21], v135 offset:512
	ds_read_b128 v[34:37], v135 offset:2048
	ds_read_b128 v[38:41], v135 offset:2560
	s_add_i32 s50, s48, -1
	v_lshlrev_b32_e32 v1, 1, v42
	v_lshlrev_b32_e32 v42, 3, v133
	s_add_u32 s6, s6, 0x8000
	s_addc_u32 s7, s7, 0
	v_and_b32_e32 v1, 32, v1
	s_add_u32 s40, s40, 0x8000
	s_mov_b32 s49, 4
	s_mov_b32 s8, 1
	s_mov_b32 s54, 0
	s_addc_u32 s41, s41, 0
	s_waitcnt vmcnt(3) lgkmcnt(3)
	v_mfma_f32_32x32x16_bf16 v[2:17], v[2:5], v[124:127], 0
	s_waitcnt lgkmcnt(2)
	v_mfma_f32_32x32x16_bf16 v[18:33], v[18:21], v[124:127], 0
	s_waitcnt vmcnt(2) lgkmcnt(1)
	v_mfma_f32_32x32x16_bf16 v[2:17], v[34:37], v[120:123], v[2:17]
	s_waitcnt lgkmcnt(0)
	v_mfma_f32_32x32x16_bf16 v[18:33], v[38:41], v[120:123], v[18:33]
	ds_read_b128 v[34:37], v135 offset:4096
	ds_read_b128 v[38:41], v135 offset:4608
	s_waitcnt vmcnt(1) lgkmcnt(1)
	v_mfma_f32_32x32x16_bf16 v[2:17], v[34:37], v[116:119], v[2:17]
	ds_read_b128 v[34:37], v135 offset:6144
	s_waitcnt lgkmcnt(1)
	v_mfma_f32_32x32x16_bf16 v[18:33], v[38:41], v[116:119], v[18:33]
	ds_read_b128 v[38:41], v135 offset:6656
	s_waitcnt vmcnt(0) lgkmcnt(1)
	v_mfma_f32_32x32x16_bf16 v[2:17], v[34:37], v[112:115], v[2:17]
	v_and_b32_e32 v34, 24, v42
	v_and_b32_e32 v35, 0xc0, v43
	v_and_b32_e32 v36, 0x100, v42
	v_add3_u32 v34, 0, v34, v35
	v_add3_u32 v1, v34, v1, v36
	s_nop 6
	v_exp_f32_e32 v64, v2
	s_waitcnt lgkmcnt(0)
; template <int NCB, bool DIFF, bool STAT>
; __device__ __forceinline__ void attn_unit(LAS char* lds, const Params& P, int s, int head, int qb, float sref) {
;     ...
;         if constexpr (!STAT) rowmax_decide<DIFF, true>(pA0, pA1, m_reg, alA, moved, bm, tab, ix); else moved = false;
; #pragma unroll
;         for (int r = 0; r < 16; ++r) { pA0[r] = __builtin_amdgcn_exp2f(pA0[r]); pA1[r] = __builtin_amdgcn_exp2f(pA1[r]); }
;         int sl_prev = 0, sl_cur = 1;
;         bf16x8 kf[3];
	v_mfma_f32_32x32x16_bf16 v[18:33], v[38:41], v[112:115], v[18:33]
	v_exp_f32_e32 v65, v3
	v_exp_f32_e32 v66, v4
	v_exp_f32_e32 v67, v5
	v_exp_f32_e32 v68, v6
	v_exp_f32_e32 v69, v7
	v_exp_f32_e32 v70, v8
	v_exp_f32_e32 v71, v9
	s_nop 4
	v_exp_f32_e32 v48, v18
	v_exp_f32_e32 v49, v19
	v_exp_f32_e32 v50, v20
	v_exp_f32_e32 v51, v21
	v_exp_f32_e32 v52, v22
	v_exp_f32_e32 v53, v23
	v_exp_f32_e32 v54, v24
	v_exp_f32_e32 v55, v25
	v_exp_f32_e32 v56, v26
	v_exp_f32_e32 v57, v27
	v_exp_f32_e32 v58, v28
	v_exp_f32_e32 v59, v29
	v_exp_f32_e32 v60, v30
	v_exp_f32_e32 v61, v31
	v_exp_f32_e32 v62, v32
	v_exp_f32_e32 v63, v33
	v_exp_f32_e32 v72, v10
	v_exp_f32_e32 v73, v11
	v_exp_f32_e32 v74, v12
	v_exp_f32_e32 v75, v13
	v_exp_f32_e32 v76, v14
	v_exp_f32_e32 v77, v15
	v_exp_f32_e32 v78, v16
	v_exp_f32_e32 v79, v17
	v_mov_b32_e32 v14, 0
	v_mov_b32_e32 v144, 0
	v_mov_b32_e32 v145, 0
	v_mov_b32_e32 v146, 0
	v_mov_b32_e32 v147, 0
	v_and_b32_e32 v140, 15, v230
	v_bfe_u32 v141, v230, 4, 1
	v_mov_b32_e32 v142, 0x3f803f80
	v_cmp_eq_u32_e64 s[98:99], v140, v141
	s_nop 1
	v_cndmask_b32_e64 v140, 0, v142, s[98:99]
	v_mov_b32_e32 v141, v140
	v_mov_b32_e32 v142, v140
	v_mov_b32_e32 v143, v140
	v_mov_b32_e32 v16, 0
	v_mov_b32_e32 v17, v14
	v_mov_b32_e32 v18, v14
	v_mov_b32_e32 v19, v14
	v_mov_b32_e32 v20, v14
	v_mov_b32_e32 v21, v14
	v_mov_b32_e32 v22, v14
	v_mov_b32_e32 v23, v14
	v_mov_b32_e32 v24, v14
	v_mov_b32_e32 v25, v14
	v_mov_b32_e32 v26, v14
	v_mov_b32_e32 v27, v14
	v_mov_b32_e32 v28, v14
	v_mov_b32_e32 v29, v14
	v_mov_b32_e32 v30, v14
	v_mov_b32_e32 v31, v14
	v_mov_b32_e32 v32, 0
	v_mov_b32_e32 v33, v14
	v_mov_b32_e32 v34, v14
	v_mov_b32_e32 v35, v14
	v_mov_b32_e32 v36, v14
	v_mov_b32_e32 v37, v14
	v_mov_b32_e32 v38, v14
	v_mov_b32_e32 v39, v14
	v_mov_b32_e32 v40, v14
	v_mov_b32_e32 v41, v14
	v_mov_b32_e32 v42, v14
	v_mov_b32_e32 v43, v14
	v_mov_b32_e32 v44, v14
	v_mov_b32_e32 v45, v14
	v_mov_b32_e32 v46, v14
	v_mov_b32_e32 v47, v14
	s_lshl_b32 s12, s54, 14
	v_lshl_add_u32 v136, s8, 13, v135
	v_add_u32_e32 v15, s12, v1
	s_branch .LBB0_591
.LBB0_590:
	s_waitcnt lgkmcnt(2)
	v_mfma_f32_32x32x16_bf16 v[16:31], v[128:131], v[48:51], v[16:31]
	ds_read_b64_tr_b16 v[56:57], v15 offset:2048
	ds_read_b64_tr_b16 v[58:59], v15 offset:3072
	v_mfma_f32_16x16x32_bf16 v[144:147], v[2:5], v[140:143], v[144:147]
	v_exp_f32_e32 v96, v96
	v_exp_f32_e32 v97, v97
	v_exp_f32_e32 v98, v98
	v_exp_f32_e32 v99, v99
	s_waitcnt lgkmcnt(2)
	v_mfma_f32_32x32x16_bf16 v[32:47], v[128:131], v[52:55], v[32:47]
	ds_read_b64_tr_b16 v[48:49], v15 offset:2560
	ds_read_b64_tr_b16 v[50:51], v15 offset:3584
	v_exp_f32_e32 v100, v100
	v_exp_f32_e32 v101, v101
	v_exp_f32_e32 v102, v102
	v_exp_f32_e32 v103, v103
	s_waitcnt lgkmcnt(2)
	v_mfma_f32_32x32x16_bf16 v[16:31], v[10:13], v[56:59], v[16:31]
	ds_read_b64_tr_b16 v[52:53], v15 offset:4096
	ds_read_b64_tr_b16 v[54:55], v15 offset:5120
	v_exp_f32_e32 v104, v104
	v_exp_f32_e32 v105, v105
	v_exp_f32_e32 v106, v106
	v_exp_f32_e32 v107, v107
	s_waitcnt lgkmcnt(2)
	v_mfma_f32_32x32x16_bf16 v[32:47], v[10:13], v[48:51], v[32:47]
	ds_read_b64_tr_b16 v[56:57], v15 offset:4608
	ds_read_b64_tr_b16 v[58:59], v15 offset:5632
	v_exp_f32_e32 v108, v108
	v_exp_f32_e32 v109, v109
	v_exp_f32_e32 v110, v110
	v_exp_f32_e32 v111, v111
	s_waitcnt lgkmcnt(2)
	v_mfma_f32_32x32x16_bf16 v[16:31], v[6:9], v[52:55], v[16:31]
	ds_read_b64_tr_b16 v[10:11], v15 offset:6144
	ds_read_b64_tr_b16 v[12:13], v15 offset:7168
	v_exp_f32_e32 v80, v80
	v_exp_f32_e32 v81, v81
	v_exp_f32_e32 v82, v82
	v_exp_f32_e32 v83, v83
	s_waitcnt lgkmcnt(2)
	v_mfma_f32_32x32x16_bf16 v[32:47], v[6:9], v[56:59], v[32:47]
	ds_read_b64_tr_b16 v[48:49], v15 offset:6656
	ds_read_b64_tr_b16 v[50:51], v15 offset:7680
	v_exp_f32_e32 v84, v84
	v_exp_f32_e32 v85, v85
	v_exp_f32_e32 v86, v86
	v_exp_f32_e32 v87, v87
	s_waitcnt lgkmcnt(2)
	v_mfma_f32_32x32x16_bf16 v[16:31], v[2:5], v[10:13], v[16:31]
	v_exp_f32_e32 v88, v88
	v_exp_f32_e32 v89, v89
	v_exp_f32_e32 v90, v90
	v_exp_f32_e32 v91, v91
	s_waitcnt lgkmcnt(0)
	v_mfma_f32_32x32x16_bf16 v[32:47], v[2:5], v[48:51], v[32:47]
	v_exp_f32_e32 v92, v92
	v_exp_f32_e32 v93, v93
	v_exp_f32_e32 v94, v94
	v_exp_f32_e32 v95, v95
	s_add_i32 s12, s8, -4
	s_add_i32 s13, s8, 1
	s_cmp_gt_i32 s8, 3
	s_cselect_b32 s12, s12, s13
	v_lshl_add_u32 v6, s12, 13, v135
	ds_read_b128 v[2:5], v6
	ds_read_b128 v[6:9], v6 offset:512
	s_cmp_lg_u32 s8, 4
	s_cselect_b32 s54, s13, 0
	v_lshl_add_u32 v15, s54, 13, v135
	v_lshl_add_u32 v128, s8, 14, v1
	s_waitcnt lgkmcnt(1)
	v_mfma_f32_32x32x16_bf16 v[64:79], v[2:5], v[124:127], 0
	ds_read_b128 v[10:13], v15 offset:2048
	v_cvt_pk_bf16_f32 v2, v96, v97
	v_cvt_pk_bf16_f32 v3, v98, v99
	s_nop 0
	ds_read_b128 v[96:99], v15 offset:2560
	v_cvt_pk_bf16_f32 v4, v100, v101
	s_waitcnt lgkmcnt(2)
	v_mfma_f32_32x32x16_bf16 v[48:63], v[6:9], v[124:127], 0
	v_cvt_pk_bf16_f32 v5, v102, v103
	s_waitcnt lgkmcnt(1)
	v_mfma_f32_32x32x16_bf16 v[64:79], v[10:13], v[120:123], v[64:79]
	ds_read_b128 v[6:9], v15 offset:4096
	v_mfma_f32_16x16x32_bf16 v[144:147], v[2:5], v[140:143], v[144:147]
	v_cvt_pk_bf16_f32 v10, v104, v105
	v_cvt_pk_bf16_f32 v11, v106, v107
	s_waitcnt lgkmcnt(1)
	v_mfma_f32_32x32x16_bf16 v[48:63], v[96:99], v[120:123], v[48:63]
	ds_read_b128 v[100:103], v15 offset:4608
	v_cvt_pk_bf16_f32 v12, v108, v109
	v_cvt_pk_bf16_f32 v13, v110, v111
	s_waitcnt lgkmcnt(1)
	v_mfma_f32_32x32x16_bf16 v[64:79], v[6:9], v[116:119], v[64:79]
	ds_read_b128 v[96:99], v15 offset:6144
	v_mfma_f32_16x16x32_bf16 v[144:147], v[10:13], v[140:143], v[144:147]
	v_cvt_pk_bf16_f32 v6, v80, v81
	v_cvt_pk_bf16_f32 v7, v82, v83
	s_waitcnt lgkmcnt(1)
	v_mfma_f32_32x32x16_bf16 v[48:63], v[100:103], v[116:119], v[48:63]
	ds_read_b128 v[80:83], v15 offset:6656
	v_cvt_pk_bf16_f32 v8, v84, v85
	v_cvt_pk_bf16_f32 v9, v86, v87
	s_waitcnt lgkmcnt(1)
	v_mfma_f32_32x32x16_bf16 v[64:79], v[96:99], v[112:115], v[64:79]
	v_cvt_pk_bf16_f32 v84, v88, v89
	v_cvt_pk_bf16_f32 v85, v90, v91
	v_mfma_f32_16x16x32_bf16 v[144:147], v[6:9], v[140:143], v[144:147]
	ds_read_b64_tr_b16 v[88:89], v128
	ds_read_b64_tr_b16 v[90:91], v128 offset:1024
	s_waitcnt lgkmcnt(2)
	v_mfma_f32_32x32x16_bf16 v[48:63], v[80:83], v[112:115], v[48:63]
	v_cvt_pk_bf16_f32 v86, v92, v93
	v_cvt_pk_bf16_f32 v87, v94, v95
	ds_read_b64_tr_b16 v[80:81], v128 offset:512
	ds_read_b64_tr_b16 v[82:83], v128 offset:1536
	s_waitcnt lgkmcnt(2)
	v_mfma_f32_32x32x16_bf16 v[16:31], v[2:5], v[88:91], v[16:31]
	ds_read_b64_tr_b16 v[92:93], v128 offset:2048
	ds_read_b64_tr_b16 v[94:95], v128 offset:3072
	v_mfma_f32_16x16x32_bf16 v[144:147], v[84:87], v[140:143], v[144:147]
	v_exp_f32_e32 v64, v64
	v_exp_f32_e32 v65, v65
	v_exp_f32_e32 v66, v66
	v_exp_f32_e32 v67, v67
	s_waitcnt lgkmcnt(2)
	v_mfma_f32_32x32x16_bf16 v[32:47], v[2:5], v[80:83], v[32:47]
	ds_read_b64_tr_b16 v[88:89], v128 offset:2560
	ds_read_b64_tr_b16 v[90:91], v128 offset:3584
	v_exp_f32_e32 v68, v68
	v_exp_f32_e32 v69, v69
	v_exp_f32_e32 v70, v70
	v_exp_f32_e32 v71, v71
	s_waitcnt lgkmcnt(2)
	v_mfma_f32_32x32x16_bf16 v[16:31], v[10:13], v[92:95], v[16:31]
	ds_read_b64_tr_b16 v[2:3], v128 offset:4096
	ds_read_b64_tr_b16 v[4:5], v128 offset:5120
	v_exp_f32_e32 v72, v72
	v_exp_f32_e32 v73, v73
	v_exp_f32_e32 v74, v74
	v_exp_f32_e32 v75, v75
	s_waitcnt lgkmcnt(2)
	v_mfma_f32_32x32x16_bf16 v[32:47], v[10:13], v[88:91], v[32:47]
	ds_read_b64_tr_b16 v[80:81], v128 offset:4608
	ds_read_b64_tr_b16 v[82:83], v128 offset:5632
	v_exp_f32_e32 v76, v76
	v_exp_f32_e32 v77, v77
	v_exp_f32_e32 v78, v78
	v_exp_f32_e32 v79, v79
	s_waitcnt lgkmcnt(2)
	v_mfma_f32_32x32x16_bf16 v[16:31], v[6:9], v[2:5], v[16:31]
	ds_read_b64_tr_b16 v[10:11], v128 offset:6144
	ds_read_b64_tr_b16 v[12:13], v128 offset:7168
	v_exp_f32_e32 v48, v48
	v_exp_f32_e32 v49, v49
	v_exp_f32_e32 v50, v50
	v_exp_f32_e32 v51, v51
	s_waitcnt lgkmcnt(2)
	v_mfma_f32_32x32x16_bf16 v[32:47], v[6:9], v[80:83], v[32:47]
	ds_read_b64_tr_b16 v[2:3], v128 offset:6656
	ds_read_b64_tr_b16 v[4:5], v128 offset:7680
	v_exp_f32_e32 v52, v52
	v_exp_f32_e32 v53, v53
	v_exp_f32_e32 v54, v54
	v_exp_f32_e32 v55, v55
	s_waitcnt lgkmcnt(2)
	v_mfma_f32_32x32x16_bf16 v[16:31], v[84:87], v[10:13], v[16:31]
	v_exp_f32_e32 v56, v56
	v_exp_f32_e32 v57, v57
	v_exp_f32_e32 v58, v58
	v_exp_f32_e32 v59, v59
	s_waitcnt lgkmcnt(0)
	v_mfma_f32_32x32x16_bf16 v[32:47], v[84:87], v[2:5], v[32:47]
	v_exp_f32_e32 v60, v60
	v_exp_f32_e32 v61, v61
	v_exp_f32_e32 v62, v62
	v_exp_f32_e32 v63, v63
	s_add_i32 s8, s54, 1
	s_cmp_lg_u32 s54, 4
	s_cselect_b32 s8, s8, 0
	s_add_u32 s6, s6, 0x4000
	s_addc_u32 s7, s7, 0
	s_add_u32 s40, s40, 0x4000
	s_addc_u32 s41, s41, 0
	s_add_i32 s49, s49, 2
	s_lshl_b32 s12, s54, 14
	v_lshl_add_u32 v136, s8, 13, v135
	v_add_u32_e32 v15, s12, v1
	s_cmp_lt_u32 s51, s50
	s_waitcnt vmcnt(0) lgkmcnt(0)
	s_barrier
	s_cbranch_scc0 .LBB0_596
.LBB0_591:
	ds_read_b128 v[2:5], v136
	ds_read_b128 v[6:9], v136 offset:512
	s_waitcnt lgkmcnt(1)
	v_mfma_f32_32x32x16_bf16 v[96:111], v[2:5], v[124:127], 0
	ds_read_b128 v[10:13], v136 offset:2048
	v_cvt_pk_bf16_f32 v128, v64, v65
	v_cvt_pk_bf16_f32 v129, v66, v67
	s_waitcnt lgkmcnt(1)
	v_mfma_f32_32x32x16_bf16 v[80:95], v[6:9], v[124:127], 0
	ds_read_b128 v[2:5], v136 offset:2560
	v_cvt_pk_bf16_f32 v130, v68, v69
	v_cvt_pk_bf16_f32 v131, v70, v71
	s_waitcnt lgkmcnt(1)
	v_mfma_f32_32x32x16_bf16 v[96:111], v[10:13], v[120:123], v[96:111]
	ds_read_b128 v[6:9], v136 offset:4096
	v_mfma_f32_16x16x32_bf16 v[144:147], v[128:131], v[140:143], v[144:147]
	v_cvt_pk_bf16_f32 v10, v72, v73
	v_cvt_pk_bf16_f32 v11, v74, v75
	s_waitcnt lgkmcnt(1)
	v_mfma_f32_32x32x16_bf16 v[80:95], v[2:5], v[120:123], v[80:95]
	ds_read_b128 v[64:67], v136 offset:4608
	v_cvt_pk_bf16_f32 v12, v76, v77
	v_cvt_pk_bf16_f32 v13, v78, v79
	s_waitcnt lgkmcnt(1)
	v_mfma_f32_32x32x16_bf16 v[96:111], v[6:9], v[116:119], v[96:111]
	ds_read_b128 v[2:5], v136 offset:6144
	v_mfma_f32_16x16x32_bf16 v[144:147], v[10:13], v[140:143], v[144:147]
	v_cvt_pk_bf16_f32 v6, v48, v49
	v_cvt_pk_bf16_f32 v7, v50, v51
	s_waitcnt lgkmcnt(1)
	v_mfma_f32_32x32x16_bf16 v[80:95], v[64:67], v[116:119], v[80:95]
	ds_read_b128 v[68:71], v136 offset:6656
	v_cvt_pk_bf16_f32 v8, v52, v53
	v_cvt_pk_bf16_f32 v9, v54, v55
	s_waitcnt lgkmcnt(1)
	v_mfma_f32_32x32x16_bf16 v[96:111], v[2:5], v[112:115], v[96:111]
	v_cvt_pk_bf16_f32 v2, v56, v57
	v_cvt_pk_bf16_f32 v3, v58, v59
	v_mfma_f32_16x16x32_bf16 v[144:147], v[6:9], v[140:143], v[144:147]
	ds_read_b64_tr_b16 v[48:49], v15
	ds_read_b64_tr_b16 v[50:51], v15 offset:1024
	s_waitcnt lgkmcnt(2)
	v_mfma_f32_32x32x16_bf16 v[80:95], v[68:71], v[112:115], v[80:95]
	v_cvt_pk_bf16_f32 v4, v60, v61
	v_cvt_pk_bf16_f32 v5, v62, v63
	ds_read_b64_tr_b16 v[52:53], v15 offset:512
	ds_read_b64_tr_b16 v[54:55], v15 offset:1536
	s_add_i32 s51, s49, -1
	s_cmp_ge_u32 s51, s48
	s_cbranch_scc1 .LBB0_593
	s_add_u32 s12, s40, 0xffffe000
	s_addc_u32 s13, s41, -1
	s_cmp_gt_i32 s8, 2
	s_cselect_b32 s54, -3, 2
	s_add_i32 s54, s54, s8
	s_lshl_b32 s55, s54, 13
	s_add_i32 s55, s55, s46
	s_mov_b32 m0, s55
	s_nop 0
	global_load_lds_dwordx4 v134, s[12:13]
	s_add_u32 s12, s6, 0xffffe000
	s_addc_u32 s13, s7, -1
	s_lshl_b32 s54, s54, 14
	s_add_i32 s54, s54, s47
	s_mov_b32 m0, s54
	s_nop 0
	global_load_lds_dwordx4 v134, s[12:13]
